# v6: +Wf-fold loop rewritten (prefetched M, v_fmac, no v_mov shuffle), rpb->LDS copy loads batched, in-proj fused-norm rss loads batched, pool window loads batched
# speedup vs baseline: 1.0232x; 1.0232x over previous
.LBB0_176:
	s_lshl_b32 s4, s18, 1
	s_ashr_i32 s35, s18, 10
	s_lshr_b32 s36, s18, 9
	s_bfe_u32 s37, s18, 0x10009
	s_and_b32 s38, s4, 0x300
	s_mul_i32 s5, s35, 0x1800000
	s_mul_hi_i32 s4, s35, 0x1800000
	s_add_u32 s5, s14, s5
	s_addc_u32 s16, s15, s4
	s_lshl_b32 s4, s18, 3
	s_and_b32 s12, s4, 0x3f8
	s_mul_i32 s4, s12, 0x6000
	s_add_u32 s4, s5, s4
	s_addc_u32 s5, s16, 0
	v_lshl_add_u64 v[24:25], s[4:5], 0, v[132:133]
	v_add_co_u32_e32 v0, vcc, s22, v24
	s_lshl_b32 s4, s35, 1
	s_nop 0
	v_addc_co_u32_e32 v1, vcc, 0, v25, vcc
	v_add_co_u32_e32 v4, vcc, s23, v24
	s_or_b32 s4, s4, s37
	s_nop 0
	v_addc_co_u32_e32 v5, vcc, 0, v25, vcc
	v_add_co_u32_e32 v8, vcc, s24, v24
	global_load_dwordx4 v[0:3], v[0:1], off
	s_nop 0
	global_load_dwordx4 v[4:7], v[4:5], off
	v_addc_co_u32_e32 v9, vcc, 0, v25, vcc
	v_add_co_u32_e32 v12, vcc, s25, v24
	s_ashr_i32 s5, s4, 31
	s_nop 0
	v_addc_co_u32_e32 v13, vcc, 0, v25, vcc
	v_add_co_u32_e32 v16, vcc, s26, v24
	global_load_dwordx4 v[8:11], v[8:9], off
	s_nop 0
	global_load_dwordx4 v[12:15], v[12:13], off
	v_addc_co_u32_e32 v17, vcc, 0, v25, vcc
	v_add_co_u32_e32 v20, vcc, s27, v24
	s_lshl_b64 s[4:5], s[4:5], 18
	s_nop 0
	v_addc_co_u32_e32 v21, vcc, 0, v25, vcc
	v_add_co_u32_e32 v26, vcc, s28, v24
	global_load_dwordx4 v[16:19], v[16:17], off
	s_nop 0
	global_load_dwordx4 v[20:23], v[20:21], off
	v_addc_co_u32_e32 v27, vcc, 0, v25, vcc
	v_add_co_u32_e32 v28, vcc, s29, v24
	s_or_b32 s4, s4, s38
	s_nop 0
	v_addc_co_u32_e32 v29, vcc, 0, v25, vcc
	global_load_dwordx4 v[24:27], v[26:27], off
	s_nop 0
	global_load_dwordx4 v[28:31], v[28:29], off
	s_mov_b64 s[16:17], 0
	v_mov_b32_e32 v128, v146
	v_mov_b32_e32 v136, 0
	v_mov_b32_e32 v137, v129
	v_mov_b32_e32 v138, 0
	v_mov_b32_e32 v139, v129
	v_lshl_add_u64 v[134:135], v[130:131], 0, s[4:5]
	v_mov_b32_e32 v140, 0
	v_mov_b32_e32 v141, v129
	v_mov_b32_e32 v142, 0
	v_mov_b32_e32 v143, v129
	s_waitcnt vmcnt(7)
	ds_write_b128 v148, v[0:3]
	s_waitcnt vmcnt(6)
	ds_write_b128 v148, v[4:7] offset:1024
	s_waitcnt vmcnt(5)
	ds_write_b128 v148, v[8:11] offset:2048
	s_waitcnt vmcnt(4)
	ds_write_b128 v148, v[12:15] offset:3072
	s_waitcnt vmcnt(3)
	ds_write_b128 v148, v[16:19] offset:4096
	s_waitcnt vmcnt(2)
	ds_write_b128 v148, v[20:23] offset:5120
	s_waitcnt vmcnt(1)
	ds_write_b128 v148, v[24:27] offset:6144
	s_waitcnt vmcnt(0)
	ds_write_b128 v148, v[28:31] offset:7168
	s_add_u32 s4, s16, 0x1ff000
	s_addc_u32 s5, s17, 0
	v_lshl_add_u64 v[96:97], v[134:135], 0, s[4:5]
	s_add_u32 s4, s4, 0x2000
	s_addc_u32 s5, s5, 0
	v_lshl_add_u64 v[98:99], v[134:135], 0, s[4:5]
	global_load_dword v64, v[96:97], off offset:-4096
	global_load_dword v65, v[96:97], off offset:-3072
	global_load_dword v66, v[96:97], off offset:-2048
	global_load_dword v67, v[96:97], off offset:-1024
	global_load_dword v68, v[96:97], off
	global_load_dword v69, v[96:97], off offset:1024
	global_load_dword v70, v[96:97], off offset:2048
	global_load_dword v71, v[96:97], off offset:3072
	global_load_dword v72, v[98:99], off offset:-4096
	global_load_dword v73, v[98:99], off offset:-3072
	global_load_dword v74, v[98:99], off offset:-2048
	global_load_dword v75, v[98:99], off offset:-1024
	global_load_dword v76, v[98:99], off
	global_load_dword v77, v[98:99], off offset:1024
	global_load_dword v78, v[98:99], off offset:2048
	global_load_dword v79, v[98:99], off offset:3072
.LBB0_177:
	s_add_u32 s4, s16, 0x203000
	s_addc_u32 s5, s17, 0
	v_lshl_add_u64 v[96:97], v[134:135], 0, s[4:5]
	s_add_u32 s4, s4, 0x2000
	s_addc_u32 s5, s5, 0
	v_lshl_add_u64 v[98:99], v[134:135], 0, s[4:5]
	global_load_dword v80, v[96:97], off offset:-4096
	global_load_dword v81, v[96:97], off offset:-3072
	global_load_dword v82, v[96:97], off offset:-2048
	global_load_dword v83, v[96:97], off offset:-1024
	global_load_dword v84, v[96:97], off
	global_load_dword v85, v[96:97], off offset:1024
	global_load_dword v86, v[96:97], off offset:2048
	global_load_dword v87, v[96:97], off offset:3072
	global_load_dword v88, v[98:99], off offset:-4096
	global_load_dword v89, v[98:99], off offset:-3072
	global_load_dword v90, v[98:99], off offset:-2048
	global_load_dword v91, v[98:99], off offset:-1024
	global_load_dword v92, v[98:99], off
	global_load_dword v93, v[98:99], off offset:1024
	global_load_dword v94, v[98:99], off offset:2048
	global_load_dword v95, v[98:99], off offset:3072
	ds_read_b128 v[0:3], v128
	ds_read_b128 v[4:7], v128 offset:1024
	ds_read_b128 v[8:11], v128 offset:2048
	ds_read_b128 v[12:15], v128 offset:3072
	ds_read_b128 v[16:19], v128 offset:4096
	ds_read_b128 v[20:23], v128 offset:5120
	ds_read_b128 v[24:27], v128 offset:6144
	ds_read_b128 v[28:31], v128 offset:7168
	ds_read_b128 v[32:35], v128 offset:16
	ds_read_b128 v[36:39], v128 offset:1040
	ds_read_b128 v[40:43], v128 offset:2064
	ds_read_b128 v[44:47], v128 offset:3088
	ds_read_b128 v[48:51], v128 offset:4112
	ds_read_b128 v[52:55], v128 offset:5136
	ds_read_b128 v[56:59], v128 offset:6160
	ds_read_b128 v[60:63], v128 offset:7184
	s_waitcnt vmcnt(16)
	s_waitcnt lgkmcnt(8)
	v_fmac_f32_e32 v138, v64, v0
	v_fmac_f32_e32 v139, v64, v4
	v_fmac_f32_e32 v140, v64, v8
	v_fmac_f32_e32 v141, v64, v12
	v_fmac_f32_e32 v142, v64, v16
	v_fmac_f32_e32 v143, v64, v20
	v_fmac_f32_e32 v136, v64, v24
	v_fmac_f32_e32 v137, v64, v28
	v_fmac_f32_e32 v138, v65, v1
	v_fmac_f32_e32 v139, v65, v5
	v_fmac_f32_e32 v140, v65, v9
	v_fmac_f32_e32 v141, v65, v13
	v_fmac_f32_e32 v142, v65, v17
	v_fmac_f32_e32 v143, v65, v21
	v_fmac_f32_e32 v136, v65, v25
	v_fmac_f32_e32 v137, v65, v29
	v_fmac_f32_e32 v138, v66, v2
	v_fmac_f32_e32 v139, v66, v6
	v_fmac_f32_e32 v140, v66, v10
	v_fmac_f32_e32 v141, v66, v14
	v_fmac_f32_e32 v142, v66, v18
	v_fmac_f32_e32 v143, v66, v22
	v_fmac_f32_e32 v136, v66, v26
	v_fmac_f32_e32 v137, v66, v30
	v_fmac_f32_e32 v138, v67, v3
	v_fmac_f32_e32 v139, v67, v7
	v_fmac_f32_e32 v140, v67, v11
	v_fmac_f32_e32 v141, v67, v15
	v_fmac_f32_e32 v142, v67, v19
	v_fmac_f32_e32 v143, v67, v23
	v_fmac_f32_e32 v136, v67, v27
	v_fmac_f32_e32 v137, v67, v31
	ds_read_b128 v[0:3], v128 offset:32
	ds_read_b128 v[4:7], v128 offset:1056
	ds_read_b128 v[8:11], v128 offset:2080
	ds_read_b128 v[12:15], v128 offset:3104
	ds_read_b128 v[16:19], v128 offset:4128
	ds_read_b128 v[20:23], v128 offset:5152
	ds_read_b128 v[24:27], v128 offset:6176
	ds_read_b128 v[28:31], v128 offset:7200
	s_waitcnt lgkmcnt(8)
	v_fmac_f32_e32 v138, v68, v32
	v_fmac_f32_e32 v139, v68, v36
	v_fmac_f32_e32 v140, v68, v40
	v_fmac_f32_e32 v141, v68, v44
	v_fmac_f32_e32 v142, v68, v48
	v_fmac_f32_e32 v143, v68, v52
	v_fmac_f32_e32 v136, v68, v56
	v_fmac_f32_e32 v137, v68, v60
	v_fmac_f32_e32 v138, v69, v33
	v_fmac_f32_e32 v139, v69, v37
	v_fmac_f32_e32 v140, v69, v41
	v_fmac_f32_e32 v141, v69, v45
	v_fmac_f32_e32 v142, v69, v49
	v_fmac_f32_e32 v143, v69, v53
	v_fmac_f32_e32 v136, v69, v57
	v_fmac_f32_e32 v137, v69, v61
	v_fmac_f32_e32 v138, v70, v34
	v_fmac_f32_e32 v139, v70, v38
	v_fmac_f32_e32 v140, v70, v42
	v_fmac_f32_e32 v141, v70, v46
	v_fmac_f32_e32 v142, v70, v50
	v_fmac_f32_e32 v143, v70, v54
	v_fmac_f32_e32 v136, v70, v58
	v_fmac_f32_e32 v137, v70, v62
	v_fmac_f32_e32 v138, v71, v35
	v_fmac_f32_e32 v139, v71, v39
	v_fmac_f32_e32 v140, v71, v43
	v_fmac_f32_e32 v141, v71, v47
	v_fmac_f32_e32 v142, v71, v51
	v_fmac_f32_e32 v143, v71, v55
	v_fmac_f32_e32 v136, v71, v59
	v_fmac_f32_e32 v137, v71, v63
	ds_read_b128 v[32:35], v128 offset:48
	ds_read_b128 v[36:39], v128 offset:1072
	ds_read_b128 v[40:43], v128 offset:2096
	ds_read_b128 v[44:47], v128 offset:3120
	ds_read_b128 v[48:51], v128 offset:4144
	ds_read_b128 v[52:55], v128 offset:5168
	ds_read_b128 v[56:59], v128 offset:6192
	ds_read_b128 v[60:63], v128 offset:7216
	s_waitcnt lgkmcnt(8)
	v_fmac_f32_e32 v138, v72, v0
	v_fmac_f32_e32 v139, v72, v4
	v_fmac_f32_e32 v140, v72, v8
	v_fmac_f32_e32 v141, v72, v12
	v_fmac_f32_e32 v142, v72, v16
	v_fmac_f32_e32 v143, v72, v20
	v_fmac_f32_e32 v136, v72, v24
	v_fmac_f32_e32 v137, v72, v28
	v_fmac_f32_e32 v138, v73, v1
	v_fmac_f32_e32 v139, v73, v5
	v_fmac_f32_e32 v140, v73, v9
	v_fmac_f32_e32 v141, v73, v13
	v_fmac_f32_e32 v142, v73, v17
	v_fmac_f32_e32 v143, v73, v21
	v_fmac_f32_e32 v136, v73, v25
	v_fmac_f32_e32 v137, v73, v29
	v_fmac_f32_e32 v138, v74, v2
	v_fmac_f32_e32 v139, v74, v6
	v_fmac_f32_e32 v140, v74, v10
	v_fmac_f32_e32 v141, v74, v14
	v_fmac_f32_e32 v142, v74, v18
	v_fmac_f32_e32 v143, v74, v22
	v_fmac_f32_e32 v136, v74, v26
	v_fmac_f32_e32 v137, v74, v30
	v_fmac_f32_e32 v138, v75, v3
	v_fmac_f32_e32 v139, v75, v7
	v_fmac_f32_e32 v140, v75, v11
	v_fmac_f32_e32 v141, v75, v15
	v_fmac_f32_e32 v142, v75, v19
	v_fmac_f32_e32 v143, v75, v23
	v_fmac_f32_e32 v136, v75, v27
	v_fmac_f32_e32 v137, v75, v31
	s_waitcnt lgkmcnt(0)
	v_fmac_f32_e32 v138, v76, v32
	v_fmac_f32_e32 v139, v76, v36
	v_fmac_f32_e32 v140, v76, v40
	v_fmac_f32_e32 v141, v76, v44
	v_fmac_f32_e32 v142, v76, v48
	v_fmac_f32_e32 v143, v76, v52
	v_fmac_f32_e32 v136, v76, v56
	v_fmac_f32_e32 v137, v76, v60
	v_fmac_f32_e32 v138, v77, v33
	v_fmac_f32_e32 v139, v77, v37
	v_fmac_f32_e32 v140, v77, v41
	v_fmac_f32_e32 v141, v77, v45
	v_fmac_f32_e32 v142, v77, v49
	v_fmac_f32_e32 v143, v77, v53
	v_fmac_f32_e32 v136, v77, v57
	v_fmac_f32_e32 v137, v77, v61
	v_fmac_f32_e32 v138, v78, v34
	v_fmac_f32_e32 v139, v78, v38
	v_fmac_f32_e32 v140, v78, v42
	v_fmac_f32_e32 v141, v78, v46
	v_fmac_f32_e32 v142, v78, v50
	v_fmac_f32_e32 v143, v78, v54
	v_fmac_f32_e32 v136, v78, v58
	v_fmac_f32_e32 v137, v78, v62
	v_fmac_f32_e32 v138, v79, v35
	v_fmac_f32_e32 v139, v79, v39
	v_fmac_f32_e32 v140, v79, v43
	v_fmac_f32_e32 v141, v79, v47
	v_fmac_f32_e32 v142, v79, v51
	v_fmac_f32_e32 v143, v79, v55
	v_fmac_f32_e32 v136, v79, v59
	v_fmac_f32_e32 v137, v79, v63
	s_add_u32 s16, s16, 0x8000
	s_addc_u32 s17, s17, 0
	s_cmp_eq_u32 s16, 0x40000
	s_cbranch_scc1 .Lfold_last
	s_add_u32 s4, s16, 0x1ff000
	s_addc_u32 s5, s17, 0
	v_lshl_add_u64 v[96:97], v[134:135], 0, s[4:5]
	s_add_u32 s4, s4, 0x2000
	s_addc_u32 s5, s5, 0
	v_lshl_add_u64 v[98:99], v[134:135], 0, s[4:5]
	global_load_dword v64, v[96:97], off offset:-4096
	global_load_dword v65, v[96:97], off offset:-3072
	global_load_dword v66, v[96:97], off offset:-2048
	global_load_dword v67, v[96:97], off offset:-1024
	global_load_dword v68, v[96:97], off
	global_load_dword v69, v[96:97], off offset:1024
	global_load_dword v70, v[96:97], off offset:2048
	global_load_dword v71, v[96:97], off offset:3072
	global_load_dword v72, v[98:99], off offset:-4096
	global_load_dword v73, v[98:99], off offset:-3072
	global_load_dword v74, v[98:99], off offset:-2048
	global_load_dword v75, v[98:99], off offset:-1024
	global_load_dword v76, v[98:99], off
	global_load_dword v77, v[98:99], off offset:1024
	global_load_dword v78, v[98:99], off offset:2048
	global_load_dword v79, v[98:99], off offset:3072
	ds_read_b128 v[0:3], v128 offset:64
	ds_read_b128 v[4:7], v128 offset:1088
	ds_read_b128 v[8:11], v128 offset:2112
	ds_read_b128 v[12:15], v128 offset:3136
	ds_read_b128 v[16:19], v128 offset:4160
	ds_read_b128 v[20:23], v128 offset:5184
	ds_read_b128 v[24:27], v128 offset:6208
	ds_read_b128 v[28:31], v128 offset:7232
	ds_read_b128 v[32:35], v128 offset:80
	ds_read_b128 v[36:39], v128 offset:1104
	ds_read_b128 v[40:43], v128 offset:2128
	ds_read_b128 v[44:47], v128 offset:3152
	ds_read_b128 v[48:51], v128 offset:4176
	ds_read_b128 v[52:55], v128 offset:5200
	ds_read_b128 v[56:59], v128 offset:6224
	ds_read_b128 v[60:63], v128 offset:7248
	s_waitcnt vmcnt(16)
	s_branch .Lfold_odd
.Lfold_last:
	ds_read_b128 v[0:3], v128 offset:64
	ds_read_b128 v[4:7], v128 offset:1088
	ds_read_b128 v[8:11], v128 offset:2112
	ds_read_b128 v[12:15], v128 offset:3136
	ds_read_b128 v[16:19], v128 offset:4160
	ds_read_b128 v[20:23], v128 offset:5184
	ds_read_b128 v[24:27], v128 offset:6208
	ds_read_b128 v[28:31], v128 offset:7232
	ds_read_b128 v[32:35], v128 offset:80
	ds_read_b128 v[36:39], v128 offset:1104
	ds_read_b128 v[40:43], v128 offset:2128
	ds_read_b128 v[44:47], v128 offset:3152
	ds_read_b128 v[48:51], v128 offset:4176
	ds_read_b128 v[52:55], v128 offset:5200
	ds_read_b128 v[56:59], v128 offset:6224
	ds_read_b128 v[60:63], v128 offset:7248
	s_waitcnt vmcnt(0)
.Lfold_odd:
	s_waitcnt lgkmcnt(8)
	v_fmac_f32_e32 v138, v80, v0
	v_fmac_f32_e32 v139, v80, v4
	v_fmac_f32_e32 v140, v80, v8
	v_fmac_f32_e32 v141, v80, v12
	v_fmac_f32_e32 v142, v80, v16
	v_fmac_f32_e32 v143, v80, v20
	v_fmac_f32_e32 v136, v80, v24
	v_fmac_f32_e32 v137, v80, v28
	v_fmac_f32_e32 v138, v81, v1
	v_fmac_f32_e32 v139, v81, v5
	v_fmac_f32_e32 v140, v81, v9
	v_fmac_f32_e32 v141, v81, v13
	v_fmac_f32_e32 v142, v81, v17
	v_fmac_f32_e32 v143, v81, v21
	v_fmac_f32_e32 v136, v81, v25
	v_fmac_f32_e32 v137, v81, v29
	v_fmac_f32_e32 v138, v82, v2
	v_fmac_f32_e32 v139, v82, v6
	v_fmac_f32_e32 v140, v82, v10
	v_fmac_f32_e32 v141, v82, v14
	v_fmac_f32_e32 v142, v82, v18
	v_fmac_f32_e32 v143, v82, v22
	v_fmac_f32_e32 v136, v82, v26
	v_fmac_f32_e32 v137, v82, v30
	v_fmac_f32_e32 v138, v83, v3
	v_fmac_f32_e32 v139, v83, v7
	v_fmac_f32_e32 v140, v83, v11
	v_fmac_f32_e32 v141, v83, v15
	v_fmac_f32_e32 v142, v83, v19
	v_fmac_f32_e32 v143, v83, v23
	v_fmac_f32_e32 v136, v83, v27
	v_fmac_f32_e32 v137, v83, v31
	ds_read_b128 v[0:3], v128 offset:96
	ds_read_b128 v[4:7], v128 offset:1120
	ds_read_b128 v[8:11], v128 offset:2144
	ds_read_b128 v[12:15], v128 offset:3168
	ds_read_b128 v[16:19], v128 offset:4192
	ds_read_b128 v[20:23], v128 offset:5216
	ds_read_b128 v[24:27], v128 offset:6240
	ds_read_b128 v[28:31], v128 offset:7264
	s_waitcnt lgkmcnt(8)
	v_fmac_f32_e32 v138, v84, v32
	v_fmac_f32_e32 v139, v84, v36
	v_fmac_f32_e32 v140, v84, v40
	v_fmac_f32_e32 v141, v84, v44
	v_fmac_f32_e32 v142, v84, v48
	v_fmac_f32_e32 v143, v84, v52
	v_fmac_f32_e32 v136, v84, v56
	v_fmac_f32_e32 v137, v84, v60
	v_fmac_f32_e32 v138, v85, v33
	v_fmac_f32_e32 v139, v85, v37
	v_fmac_f32_e32 v140, v85, v41
	v_fmac_f32_e32 v141, v85, v45
	v_fmac_f32_e32 v142, v85, v49
	v_fmac_f32_e32 v143, v85, v53
	v_fmac_f32_e32 v136, v85, v57
	v_fmac_f32_e32 v137, v85, v61
	v_fmac_f32_e32 v138, v86, v34
	v_fmac_f32_e32 v139, v86, v38
	v_fmac_f32_e32 v140, v86, v42
	v_fmac_f32_e32 v141, v86, v46
	v_fmac_f32_e32 v142, v86, v50
	v_fmac_f32_e32 v143, v86, v54
	v_fmac_f32_e32 v136, v86, v58
	v_fmac_f32_e32 v137, v86, v62
	v_fmac_f32_e32 v138, v87, v35
	v_fmac_f32_e32 v139, v87, v39
	v_fmac_f32_e32 v140, v87, v43
	v_fmac_f32_e32 v141, v87, v47
	v_fmac_f32_e32 v142, v87, v51
	v_fmac_f32_e32 v143, v87, v55
	v_fmac_f32_e32 v136, v87, v59
	v_fmac_f32_e32 v137, v87, v63
	ds_read_b128 v[32:35], v128 offset:112
	ds_read_b128 v[36:39], v128 offset:1136
	ds_read_b128 v[40:43], v128 offset:2160
	ds_read_b128 v[44:47], v128 offset:3184
	ds_read_b128 v[48:51], v128 offset:4208
	ds_read_b128 v[52:55], v128 offset:5232
	ds_read_b128 v[56:59], v128 offset:6256
	ds_read_b128 v[60:63], v128 offset:7280
	s_waitcnt lgkmcnt(8)
	v_fmac_f32_e32 v138, v88, v0
	v_fmac_f32_e32 v139, v88, v4
	v_fmac_f32_e32 v140, v88, v8
	v_fmac_f32_e32 v141, v88, v12
	v_fmac_f32_e32 v142, v88, v16
	v_fmac_f32_e32 v143, v88, v20
	v_fmac_f32_e32 v136, v88, v24
	v_fmac_f32_e32 v137, v88, v28
	v_fmac_f32_e32 v138, v89, v1
	v_fmac_f32_e32 v139, v89, v5
	v_fmac_f32_e32 v140, v89, v9
	v_fmac_f32_e32 v141, v89, v13
	v_fmac_f32_e32 v142, v89, v17
	v_fmac_f32_e32 v143, v89, v21
	v_fmac_f32_e32 v136, v89, v25
	v_fmac_f32_e32 v137, v89, v29
	v_fmac_f32_e32 v138, v90, v2
	v_fmac_f32_e32 v139, v90, v6
	v_fmac_f32_e32 v140, v90, v10
	v_fmac_f32_e32 v141, v90, v14
	v_fmac_f32_e32 v142, v90, v18
	v_fmac_f32_e32 v143, v90, v22
	v_fmac_f32_e32 v136, v90, v26
	v_fmac_f32_e32 v137, v90, v30
	v_fmac_f32_e32 v138, v91, v3
	v_fmac_f32_e32 v139, v91, v7
	v_fmac_f32_e32 v140, v91, v11
	v_fmac_f32_e32 v141, v91, v15
	v_fmac_f32_e32 v142, v91, v19
	v_fmac_f32_e32 v143, v91, v23
	v_fmac_f32_e32 v136, v91, v27
	v_fmac_f32_e32 v137, v91, v31
	s_waitcnt lgkmcnt(0)
	v_fmac_f32_e32 v138, v92, v32
	v_fmac_f32_e32 v139, v92, v36
	v_fmac_f32_e32 v140, v92, v40
	v_fmac_f32_e32 v141, v92, v44
	v_fmac_f32_e32 v142, v92, v48
	v_fmac_f32_e32 v143, v92, v52
	v_fmac_f32_e32 v136, v92, v56
	v_fmac_f32_e32 v137, v92, v60
	v_fmac_f32_e32 v138, v93, v33
	v_fmac_f32_e32 v139, v93, v37
	v_fmac_f32_e32 v140, v93, v41
	v_fmac_f32_e32 v141, v93, v45
	v_fmac_f32_e32 v142, v93, v49
	v_fmac_f32_e32 v143, v93, v53
	v_fmac_f32_e32 v136, v93, v57
	v_fmac_f32_e32 v137, v93, v61
	v_fmac_f32_e32 v138, v94, v34
	v_fmac_f32_e32 v139, v94, v38
	v_fmac_f32_e32 v140, v94, v42
	v_fmac_f32_e32 v141, v94, v46
	v_fmac_f32_e32 v142, v94, v50
	v_fmac_f32_e32 v143, v94, v54
	v_fmac_f32_e32 v136, v94, v58
	v_fmac_f32_e32 v137, v94, v62
	v_fmac_f32_e32 v138, v95, v35
	v_fmac_f32_e32 v139, v95, v39
	v_fmac_f32_e32 v140, v95, v43
	v_fmac_f32_e32 v141, v95, v47
	v_fmac_f32_e32 v142, v95, v51
	v_fmac_f32_e32 v143, v95, v55
	v_fmac_f32_e32 v136, v95, v59
	v_fmac_f32_e32 v137, v95, v63
	v_add_u32_e32 v128, 0x80, v128
	s_cmp_eq_u32 s16, 0x40000
	s_cbranch_scc0 .LBB0_177
	s_lshr_b32 s4, s18, 1
	s_and_b32 s16, s36, 1
	s_and_b32 s17, s4, 0xc0
	s_mul_i32 s4, s35, 0xc80000
	s_mul_hi_i32 s5, s35, 0xc80000
	s_add_u32 s4, s20, s4
	s_addc_u32 s5, s21, s5
	s_lshl_b32 s16, s16, 19
	v_or_b32_e32 v0, s17, v147
	s_add_i32 s16, s16, 0xb80000
	v_lshl_or_b32 v128, v0, 11, s16
	v_lshl_add_u64 v[0:1], s[4:5], 0, v[128:129]
	s_lshl_b32 s12, s12, 1
	s_add_i32 s18, s18, s19
	v_lshl_add_u64 v[4:5], v[0:1], 0, s[12:13]
	v_cvt_pk_bf16_f32 v0, v138, v139
	v_cvt_pk_bf16_f32 v1, v140, v141
	v_cvt_pk_bf16_f32 v2, v142, v143
	v_cvt_pk_bf16_f32 v3, v136, v137
	s_cmpk_gt_i32 s18, 0x7ff
	global_store_dwordx4 v[4:5], v[0:3], off
	s_cbranch_scc0 .LBB0_176

.LBB0_403:
	s_mov_b64 s[70:71], s[14:15]
	s_cbranch_execz .LBB0_475
	s_andn2_b64 vcc, exec, s[56:57]
	s_cbranch_vccnz .LBB0_407
	s_lshl_b32 s5, s68, 8
	s_add_i32 s10, s5, 0xfffff000
	s_lshr_b32 s10, s10, 11
	s_add_i32 s10, s10, 1
	s_cmp_gt_i32 s68, 15
	s_cselect_b32 s10, s10, 0
	s_mul_hi_u32 s11, s10, 0x6400
	s_mulk_i32 s10, 0x6400
	s_add_u32 s16, s91, s10
	s_addc_u32 s17, s92, s11
	s_lshl_b32 s10, s18, 8
	s_ashr_i32 s11, s10, 31
	s_lshl_b64 s[10:11], s[10:11], 2
	s_add_u32 s16, s16, s10
	s_addc_u32 s17, s17, s11
	s_lshl_b32 s10, s82, 5
	s_ashr_i32 s11, s10, 31
	s_lshl_b64 s[10:11], s[10:11], 2
	s_add_u32 s10, s16, s10
	v_lshlrev_b32_e32 v128, 2, v159
	s_addc_u32 s11, s17, s11
	v_ashrrev_i32_e32 v129, 31, v128
	v_lshl_add_u64 v[128:129], v[128:129], 2, s[10:11]
	s_lshl_b32 s10, s97, 6
	s_add_i32 s10, s10, s5
	v_add_u32_e32 v150, s10, v157
	v_ashrrev_i32_e32 v151, 31, v150
	v_lshl_add_u64 v[152:153], v[150:151], 2, s[50:51]
	global_load_dwordx4 v[140:143], v[128:129], off
	global_load_dwordx4 v[136:139], v[128:129], off offset:64
	global_load_dwordx4 v[132:135], v[128:129], off offset:512
	s_nop 0
	global_load_dwordx4 v[128:131], v[128:129], off offset:576
	s_nop 0
	global_load_dword v164, v[152:153], off
	v_add_u32_e32 v152, 16, v150
	v_ashrrev_i32_e32 v153, 31, v152
	v_lshl_add_u64 v[152:153], v[152:153], 2, s[50:51]
	global_load_dword v165, v[152:153], off
	v_add_u32_e32 v152, 32, v150
	v_ashrrev_i32_e32 v153, 31, v152
	v_lshl_add_u64 v[152:153], v[152:153], 2, s[50:51]
	global_load_dword v166, v[152:153], off
	v_add_u32_e32 v152, 48, v150
	v_ashrrev_i32_e32 v153, 31, v152
	v_lshl_add_u64 v[152:153], v[152:153], 2, s[50:51]
	global_load_dword v167, v[152:153], off
	v_add_u32_e32 v152, 0x80, v150
	v_ashrrev_i32_e32 v153, 31, v152
	v_lshl_add_u64 v[152:153], v[152:153], 2, s[50:51]
	global_load_dword v168, v[152:153], off
	v_add_u32_e32 v152, 0x90, v150
	v_ashrrev_i32_e32 v153, 31, v152
	v_lshl_add_u64 v[152:153], v[152:153], 2, s[50:51]
	global_load_dword v169, v[152:153], off
	v_add_u32_e32 v152, 0xa0, v150
	v_ashrrev_i32_e32 v153, 31, v152
	v_lshl_add_u64 v[152:153], v[152:153], 2, s[50:51]
	global_load_dword v170, v[152:153], off
	v_add_u32_e32 v152, 0xb0, v150
	v_ashrrev_i32_e32 v153, 31, v152
	v_lshl_add_u64 v[152:153], v[152:153], 2, s[50:51]
	global_load_dword v171, v[152:153], off
	s_waitcnt vmcnt(7)
	v_fmamk_f32 v151, v164, 0x3a800000, v194
	v_cmp_gt_f32_e32 vcc, s27, v151
	v_mul_f32_e32 v152, 0x4b800000, v151
	s_nop 0
	v_cndmask_b32_e32 v151, v151, v152, vcc
	v_rsq_f32_e32 v151, v151
	s_nop 0
	v_mul_f32_e32 v152, 0x45800000, v151
	v_cndmask_b32_e32 v152, v151, v152, vcc
	v_pk_fma_f32 v[126:127], v[126:127], v[152:153], v[142:143] op_sel_hi:[1,0,1]
	v_pk_fma_f32 v[124:125], v[124:125], v[152:153], v[140:141] op_sel_hi:[1,0,1]
	v_pk_fma_f32 v[122:123], v[122:123], v[152:153], v[138:139] op_sel_hi:[1,0,1]
	v_pk_fma_f32 v[120:121], v[120:121], v[152:153], v[136:137] op_sel_hi:[1,0,1]
	v_pk_fma_f32 v[118:119], v[118:119], v[152:153], v[134:135] op_sel_hi:[1,0,1]
	v_pk_fma_f32 v[116:117], v[116:117], v[152:153], v[132:133] op_sel_hi:[1,0,1]
	v_pk_fma_f32 v[114:115], v[114:115], v[152:153], v[130:131] op_sel_hi:[1,0,1]
	v_pk_fma_f32 v[112:113], v[112:113], v[152:153], v[128:129] op_sel_hi:[1,0,1]
	s_waitcnt vmcnt(6)
	v_fmamk_f32 v151, v165, 0x3a800000, v194
	v_cmp_gt_f32_e32 vcc, s27, v151
	v_mul_f32_e32 v152, 0x4b800000, v151
	s_nop 0
	v_cndmask_b32_e32 v151, v151, v152, vcc
	v_rsq_f32_e32 v151, v151
	s_nop 0
	v_mul_f32_e32 v152, 0x45800000, v151
	v_cndmask_b32_e32 v152, v151, v152, vcc
	v_pk_fma_f32 v[110:111], v[110:111], v[152:153], v[142:143] op_sel_hi:[1,0,1]
	v_pk_fma_f32 v[108:109], v[108:109], v[152:153], v[140:141] op_sel_hi:[1,0,1]
	v_pk_fma_f32 v[106:107], v[106:107], v[152:153], v[138:139] op_sel_hi:[1,0,1]
	v_pk_fma_f32 v[104:105], v[104:105], v[152:153], v[136:137] op_sel_hi:[1,0,1]
	v_pk_fma_f32 v[102:103], v[102:103], v[152:153], v[134:135] op_sel_hi:[1,0,1]
	v_pk_fma_f32 v[100:101], v[100:101], v[152:153], v[132:133] op_sel_hi:[1,0,1]
	v_pk_fma_f32 v[98:99], v[98:99], v[152:153], v[130:131] op_sel_hi:[1,0,1]
	v_pk_fma_f32 v[96:97], v[96:97], v[152:153], v[128:129] op_sel_hi:[1,0,1]
	s_waitcnt vmcnt(5)
	v_fmamk_f32 v151, v166, 0x3a800000, v194
	v_cmp_gt_f32_e32 vcc, s27, v151
	v_mul_f32_e32 v152, 0x4b800000, v151
	s_nop 0
	v_cndmask_b32_e32 v151, v151, v152, vcc
	v_rsq_f32_e32 v151, v151
	s_nop 0
	v_mul_f32_e32 v152, 0x45800000, v151
	v_cndmask_b32_e32 v152, v151, v152, vcc
	v_pk_fma_f32 v[94:95], v[94:95], v[152:153], v[142:143] op_sel_hi:[1,0,1]
	v_pk_fma_f32 v[92:93], v[92:93], v[152:153], v[140:141] op_sel_hi:[1,0,1]
	v_pk_fma_f32 v[90:91], v[90:91], v[152:153], v[138:139] op_sel_hi:[1,0,1]
	v_pk_fma_f32 v[88:89], v[88:89], v[152:153], v[136:137] op_sel_hi:[1,0,1]
	v_pk_fma_f32 v[86:87], v[86:87], v[152:153], v[134:135] op_sel_hi:[1,0,1]
	v_pk_fma_f32 v[84:85], v[84:85], v[152:153], v[132:133] op_sel_hi:[1,0,1]
	v_pk_fma_f32 v[82:83], v[82:83], v[152:153], v[130:131] op_sel_hi:[1,0,1]
	v_pk_fma_f32 v[80:81], v[80:81], v[152:153], v[128:129] op_sel_hi:[1,0,1]
	s_waitcnt vmcnt(4)
	v_fmamk_f32 v151, v167, 0x3a800000, v194
	v_cmp_gt_f32_e32 vcc, s27, v151
	v_mul_f32_e32 v152, 0x4b800000, v151
	s_nop 0
	v_cndmask_b32_e32 v151, v151, v152, vcc
	v_rsq_f32_e32 v151, v151
	s_nop 0
	v_mul_f32_e32 v152, 0x45800000, v151
	v_cndmask_b32_e32 v152, v151, v152, vcc
	v_pk_fma_f32 v[78:79], v[78:79], v[152:153], v[142:143] op_sel_hi:[1,0,1]
	v_pk_fma_f32 v[76:77], v[76:77], v[152:153], v[140:141] op_sel_hi:[1,0,1]
	v_pk_fma_f32 v[74:75], v[74:75], v[152:153], v[138:139] op_sel_hi:[1,0,1]
	v_pk_fma_f32 v[72:73], v[72:73], v[152:153], v[136:137] op_sel_hi:[1,0,1]
	v_pk_fma_f32 v[70:71], v[70:71], v[152:153], v[134:135] op_sel_hi:[1,0,1]
	v_pk_fma_f32 v[68:69], v[68:69], v[152:153], v[132:133] op_sel_hi:[1,0,1]
	v_pk_fma_f32 v[66:67], v[66:67], v[152:153], v[130:131] op_sel_hi:[1,0,1]
	v_pk_fma_f32 v[64:65], v[64:65], v[152:153], v[128:129] op_sel_hi:[1,0,1]
	s_waitcnt vmcnt(3)
	v_fmamk_f32 v151, v168, 0x3a800000, v194
	v_cmp_gt_f32_e32 vcc, s27, v151
	v_mul_f32_e32 v152, 0x4b800000, v151
	s_nop 0
	v_cndmask_b32_e32 v151, v151, v152, vcc
	v_rsq_f32_e32 v151, v151
	s_nop 0
	v_mul_f32_e32 v152, 0x45800000, v151
	v_cndmask_b32_e32 v152, v151, v152, vcc
	v_pk_fma_f32 v[62:63], v[62:63], v[152:153], v[142:143] op_sel_hi:[1,0,1]
	v_pk_fma_f32 v[60:61], v[60:61], v[152:153], v[140:141] op_sel_hi:[1,0,1]
	v_pk_fma_f32 v[58:59], v[58:59], v[152:153], v[138:139] op_sel_hi:[1,0,1]
	v_pk_fma_f32 v[56:57], v[56:57], v[152:153], v[136:137] op_sel_hi:[1,0,1]
	v_pk_fma_f32 v[54:55], v[54:55], v[152:153], v[134:135] op_sel_hi:[1,0,1]
	v_pk_fma_f32 v[52:53], v[52:53], v[152:153], v[132:133] op_sel_hi:[1,0,1]
	v_pk_fma_f32 v[50:51], v[50:51], v[152:153], v[130:131] op_sel_hi:[1,0,1]
	v_pk_fma_f32 v[48:49], v[48:49], v[152:153], v[128:129] op_sel_hi:[1,0,1]
	s_waitcnt vmcnt(2)
	v_fmamk_f32 v151, v169, 0x3a800000, v194
	v_cmp_gt_f32_e32 vcc, s27, v151
	v_mul_f32_e32 v152, 0x4b800000, v151
	s_nop 0
	v_cndmask_b32_e32 v151, v151, v152, vcc
	v_rsq_f32_e32 v151, v151
	s_nop 0
	v_mul_f32_e32 v152, 0x45800000, v151
	v_cndmask_b32_e32 v152, v151, v152, vcc
	v_pk_fma_f32 v[46:47], v[46:47], v[152:153], v[142:143] op_sel_hi:[1,0,1]
	v_pk_fma_f32 v[44:45], v[44:45], v[152:153], v[140:141] op_sel_hi:[1,0,1]
	v_pk_fma_f32 v[42:43], v[42:43], v[152:153], v[138:139] op_sel_hi:[1,0,1]
	v_pk_fma_f32 v[40:41], v[40:41], v[152:153], v[136:137] op_sel_hi:[1,0,1]
	v_pk_fma_f32 v[38:39], v[38:39], v[152:153], v[134:135] op_sel_hi:[1,0,1]
	v_pk_fma_f32 v[36:37], v[36:37], v[152:153], v[132:133] op_sel_hi:[1,0,1]
	v_pk_fma_f32 v[34:35], v[34:35], v[152:153], v[130:131] op_sel_hi:[1,0,1]
	v_pk_fma_f32 v[32:33], v[32:33], v[152:153], v[128:129] op_sel_hi:[1,0,1]
	s_waitcnt vmcnt(1)
	v_fmamk_f32 v151, v170, 0x3a800000, v194
	v_cmp_gt_f32_e32 vcc, s27, v151
	v_mul_f32_e32 v152, 0x4b800000, v151
	s_nop 0
	v_cndmask_b32_e32 v151, v151, v152, vcc
	v_rsq_f32_e32 v151, v151
	s_nop 0
	v_mul_f32_e32 v152, 0x45800000, v151
	v_cndmask_b32_e32 v152, v151, v152, vcc
	v_pk_fma_f32 v[30:31], v[30:31], v[152:153], v[142:143] op_sel_hi:[1,0,1]
	v_pk_fma_f32 v[28:29], v[28:29], v[152:153], v[140:141] op_sel_hi:[1,0,1]
	v_pk_fma_f32 v[26:27], v[26:27], v[152:153], v[138:139] op_sel_hi:[1,0,1]
	v_pk_fma_f32 v[24:25], v[24:25], v[152:153], v[136:137] op_sel_hi:[1,0,1]
	v_pk_fma_f32 v[22:23], v[22:23], v[152:153], v[134:135] op_sel_hi:[1,0,1]
	v_pk_fma_f32 v[20:21], v[20:21], v[152:153], v[132:133] op_sel_hi:[1,0,1]
	v_pk_fma_f32 v[18:19], v[18:19], v[152:153], v[130:131] op_sel_hi:[1,0,1]
	v_pk_fma_f32 v[16:17], v[16:17], v[152:153], v[128:129] op_sel_hi:[1,0,1]
	s_waitcnt vmcnt(0)
	v_fmamk_f32 v151, v171, 0x3a800000, v194
	v_cmp_gt_f32_e32 vcc, s27, v151
	v_mul_f32_e32 v152, 0x4b800000, v151
	s_nop 0
	v_cndmask_b32_e32 v151, v151, v152, vcc
	v_rsq_f32_e32 v151, v151
	s_nop 0
	v_mul_f32_e32 v152, 0x45800000, v151
	v_cndmask_b32_e32 v152, v151, v152, vcc
	v_pk_fma_f32 v[14:15], v[14:15], v[152:153], v[142:143] op_sel_hi:[1,0,1]
	v_pk_fma_f32 v[12:13], v[12:13], v[152:153], v[140:141] op_sel_hi:[1,0,1]
	v_pk_fma_f32 v[10:11], v[10:11], v[152:153], v[138:139] op_sel_hi:[1,0,1]
	v_pk_fma_f32 v[8:9], v[8:9], v[152:153], v[136:137] op_sel_hi:[1,0,1]
	v_pk_fma_f32 v[6:7], v[6:7], v[152:153], v[134:135] op_sel_hi:[1,0,1]
	v_pk_fma_f32 v[4:5], v[4:5], v[152:153], v[132:133] op_sel_hi:[1,0,1]
	v_pk_fma_f32 v[2:3], v[2:3], v[152:153], v[130:131] op_sel_hi:[1,0,1]
	v_pk_fma_f32 v[0:1], v[0:1], v[152:153], v[128:129] op_sel_hi:[1,0,1]
	s_cmp_gt_i32 s18, 5
	s_mov_b64 s[10:11], -1
	s_cbranch_scc1 .LBB0_408

.LBB0_568:
	s_mul_i32 s4, s88, 0x3a20
	s_add_u32 s4, s0, s4
	s_addc_u32 s5, s1, 0
	v_lshlrev_b32_e32 v144, 2, v212
	v_add_u32_e32 v145, 0x1000, v144
	v_add_u32_e32 v146, 0x2000, v144
	v_add_u32_e32 v147, 0x3000, v144
	s_movk_i32 s16, 0x88
	v_cmp_gt_u32_e32 vcc, s16, v212
	global_load_dword v148, v144, s[4:5]
	global_load_dword v149, v144, s[4:5] offset:2048
	global_load_dword v150, v145, s[4:5]
	global_load_dword v151, v145, s[4:5] offset:2048
	global_load_dword v152, v146, s[4:5]
	global_load_dword v153, v146, s[4:5] offset:2048
	global_load_dword v154, v147, s[4:5]
	s_mov_b64 s[10:11], exec
	s_and_b64 exec, exec, vcc
	global_load_dword v155, v147, s[4:5] offset:2048
	s_mov_b64 exec, s[10:11]
	s_waitcnt vmcnt(7)
	v_mul_f32_e32 v148, 0x3fb8aa3b, v148
	ds_write_b32 v144, v148 offset:256
	s_waitcnt vmcnt(6)
	v_mul_f32_e32 v149, 0x3fb8aa3b, v149
	ds_write_b32 v144, v149 offset:2304
	s_waitcnt vmcnt(5)
	v_mul_f32_e32 v150, 0x3fb8aa3b, v150
	ds_write_b32 v144, v150 offset:4352
	s_waitcnt vmcnt(4)
	v_mul_f32_e32 v151, 0x3fb8aa3b, v151
	ds_write_b32 v144, v151 offset:6400
	s_waitcnt vmcnt(3)
	v_mul_f32_e32 v152, 0x3fb8aa3b, v152
	ds_write_b32 v144, v152 offset:8448
	s_waitcnt vmcnt(2)
	v_mul_f32_e32 v153, 0x3fb8aa3b, v153
	ds_write_b32 v144, v153 offset:10496
	s_waitcnt vmcnt(1)
	v_mul_f32_e32 v154, 0x3fb8aa3b, v154
	ds_write_b32 v144, v154 offset:12544
	s_and_b64 exec, exec, vcc
	s_waitcnt vmcnt(0)
	v_mul_f32_e32 v155, 0x3fb8aa3b, v155
	ds_write_b32 v144, v155 offset:14592
	s_mov_b64 exec, s[10:11]

.LBB0_1418:
	v_add_u32_e32 v19, s12, v1
	v_add_u32_e32 v144, s12, v18
	v_ashrrev_i32_e32 v145, 31, v144
	v_lshlrev_b64 v[144:145], 9, v[144:145]
	v_lshl_add_u64 v[144:145], v[12:13], 0, v[144:145]
	v_add3_u32 v146, v18, s12, 1
	v_ashrrev_i32_e32 v147, 31, v146
	v_lshlrev_b64 v[146:147], 9, v[146:147]
	v_lshl_add_u64 v[146:147], v[12:13], 0, v[146:147]
	v_add3_u32 v148, v18, s12, 2
	v_ashrrev_i32_e32 v149, 31, v148
	v_lshlrev_b64 v[148:149], 9, v[148:149]
	v_lshl_add_u64 v[148:149], v[12:13], 0, v[148:149]
	v_add3_u32 v150, v18, s12, 3
	v_ashrrev_i32_e32 v151, 31, v150
	v_lshlrev_b64 v[150:151], 9, v[150:151]
	v_lshl_add_u64 v[150:151], v[12:13], 0, v[150:151]
	v_cmp_lt_i32_e32 vcc, v19, v16
	s_and_saveexec_b64 s[10:11], vcc
	global_load_dwordx4 v[152:155], v[144:145], off
	s_mov_b64 exec, s[10:11]
	v_add_u32_e32 v20, 1, v19
	v_cmp_lt_i32_e32 vcc, v20, v16
	s_and_saveexec_b64 s[10:11], vcc
	global_load_dwordx4 v[156:159], v[146:147], off
	s_mov_b64 exec, s[10:11]
	v_add_u32_e32 v20, 2, v19
	v_cmp_lt_i32_e32 vcc, v20, v16
	s_and_saveexec_b64 s[10:11], vcc
	global_load_dwordx4 v[160:163], v[148:149], off
	s_mov_b64 exec, s[10:11]
	v_add_u32_e32 v20, 3, v19
	v_cmp_lt_i32_e32 vcc, v20, v16
	s_and_saveexec_b64 s[10:11], vcc
	global_load_dwordx4 v[164:167], v[150:151], off
	s_mov_b64 exec, s[10:11]
	v_cmp_lt_i32_e32 vcc, v19, v16
	s_and_saveexec_b64 s[10:11], vcc
	s_waitcnt vmcnt(3)
	v_lshlrev_b32_e32 v24, 16, v152
	v_and_b32_e32 v25, 0xffff0000, v152
	v_lshlrev_b32_e32 v20, 16, v153
	v_and_b32_e32 v21, 0xffff0000, v153
	v_pk_add_f32 v[8:9], v[8:9], v[20:21]
	v_lshlrev_b32_e32 v20, 16, v154
	v_and_b32_e32 v21, 0xffff0000, v154
	v_pk_add_f32 v[6:7], v[6:7], v[20:21]
	v_lshlrev_b32_e32 v20, 16, v155
	v_and_b32_e32 v21, 0xffff0000, v155
	v_pk_add_f32 v[10:11], v[10:11], v[24:25]
	v_pk_add_f32 v[4:5], v[4:5], v[20:21]
	s_mov_b64 exec, s[10:11]
	v_add_u32_e32 v20, 1, v19
	v_cmp_lt_i32_e32 vcc, v20, v16
	s_and_saveexec_b64 s[10:11], vcc
	s_waitcnt vmcnt(2)
	v_lshlrev_b32_e32 v24, 16, v156
	v_and_b32_e32 v25, 0xffff0000, v156
	v_lshlrev_b32_e32 v20, 16, v157
	v_and_b32_e32 v21, 0xffff0000, v157
	v_pk_add_f32 v[8:9], v[8:9], v[20:21]
	v_lshlrev_b32_e32 v20, 16, v158
	v_and_b32_e32 v21, 0xffff0000, v158
	v_pk_add_f32 v[6:7], v[6:7], v[20:21]
	v_lshlrev_b32_e32 v20, 16, v159
	v_and_b32_e32 v21, 0xffff0000, v159
	v_pk_add_f32 v[10:11], v[10:11], v[24:25]
	v_pk_add_f32 v[4:5], v[4:5], v[20:21]
	s_mov_b64 exec, s[10:11]
	v_add_u32_e32 v20, 2, v19
	v_cmp_lt_i32_e32 vcc, v20, v16
	s_and_saveexec_b64 s[10:11], vcc
	s_waitcnt vmcnt(1)
	v_lshlrev_b32_e32 v24, 16, v160
	v_and_b32_e32 v25, 0xffff0000, v160
	v_lshlrev_b32_e32 v20, 16, v161
	v_and_b32_e32 v21, 0xffff0000, v161
	v_pk_add_f32 v[8:9], v[8:9], v[20:21]
	v_lshlrev_b32_e32 v20, 16, v162
	v_and_b32_e32 v21, 0xffff0000, v162
	v_pk_add_f32 v[6:7], v[6:7], v[20:21]
	v_lshlrev_b32_e32 v20, 16, v163
	v_and_b32_e32 v21, 0xffff0000, v163
	v_pk_add_f32 v[10:11], v[10:11], v[24:25]
	v_pk_add_f32 v[4:5], v[4:5], v[20:21]
	s_mov_b64 exec, s[10:11]
	v_add_u32_e32 v20, 3, v19
	v_cmp_lt_i32_e32 vcc, v20, v16
	s_and_saveexec_b64 s[10:11], vcc
	s_waitcnt vmcnt(0)
	v_lshlrev_b32_e32 v24, 16, v164
	v_and_b32_e32 v25, 0xffff0000, v164
	v_lshlrev_b32_e32 v20, 16, v165
	v_and_b32_e32 v21, 0xffff0000, v165
	v_pk_add_f32 v[8:9], v[8:9], v[20:21]
	v_lshlrev_b32_e32 v20, 16, v166
	v_and_b32_e32 v21, 0xffff0000, v166
	v_pk_add_f32 v[6:7], v[6:7], v[20:21]
	v_lshlrev_b32_e32 v20, 16, v167
	v_and_b32_e32 v21, 0xffff0000, v167
	v_pk_add_f32 v[10:11], v[10:11], v[24:25]
	v_pk_add_f32 v[4:5], v[4:5], v[20:21]
	s_mov_b64 exec, s[10:11]
	s_add_i32 s12, s12, 4
	s_cmp_lg_u32 s4, s12
	s_cbranch_scc1 .LBB0_1418
	s_branch .LBB0_1427

.LBB0_1427:
	s_and_b32 s5, s5, 3
	s_cmp_eq_u32 s5, 0
	s_cbranch_scc1 .LBB0_1413
	v_add_u32_e32 v18, s4, v1
	s_cmp_eq_u32 s5, 2
	s_cbranch_scc1 .Lpool_rem2
	s_branch .LBB0_1430
.Lpool_rem2:
	v_add_u32_e32 v144, v17, v18
	v_ashrrev_i32_e32 v145, 31, v144
	v_lshlrev_b64 v[144:145], 9, v[144:145]
	v_lshl_add_u64 v[144:145], v[12:13], 0, v[144:145]
	v_add3_u32 v146, v17, v18, 1
	v_ashrrev_i32_e32 v147, 31, v146
	v_lshlrev_b64 v[146:147], 9, v[146:147]
	v_lshl_add_u64 v[146:147], v[12:13], 0, v[146:147]
	v_add_u32_e32 v19, 1, v18
	v_cmp_lt_i32_e32 vcc, v18, v16
	s_and_saveexec_b64 s[10:11], vcc
	global_load_dwordx4 v[152:155], v[144:145], off
	s_mov_b64 exec, s[10:11]
	v_cmp_lt_i32_e32 vcc, v19, v16
	s_and_saveexec_b64 s[10:11], vcc
	global_load_dwordx4 v[156:159], v[146:147], off
	s_mov_b64 exec, s[10:11]
	v_cmp_lt_i32_e32 vcc, v18, v16
	s_and_saveexec_b64 s[10:11], vcc
	s_waitcnt vmcnt(1)
	v_lshlrev_b32_e32 v24, 16, v152
	v_and_b32_e32 v25, 0xffff0000, v152
	v_lshlrev_b32_e32 v20, 16, v153
	v_and_b32_e32 v21, 0xffff0000, v153
	v_pk_add_f32 v[8:9], v[8:9], v[20:21]
	v_lshlrev_b32_e32 v20, 16, v154
	v_and_b32_e32 v21, 0xffff0000, v154
	v_pk_add_f32 v[6:7], v[6:7], v[20:21]
	v_lshlrev_b32_e32 v20, 16, v155
	v_and_b32_e32 v21, 0xffff0000, v155
	v_pk_add_f32 v[10:11], v[10:11], v[24:25]
	v_pk_add_f32 v[4:5], v[4:5], v[20:21]
	s_mov_b64 exec, s[10:11]
	v_cmp_lt_i32_e32 vcc, v19, v16
	s_and_saveexec_b64 s[10:11], vcc
	s_waitcnt vmcnt(0)
	v_lshlrev_b32_e32 v24, 16, v156
	v_and_b32_e32 v25, 0xffff0000, v156
	v_lshlrev_b32_e32 v20, 16, v157
	v_and_b32_e32 v21, 0xffff0000, v157
	v_pk_add_f32 v[8:9], v[8:9], v[20:21]
	v_lshlrev_b32_e32 v20, 16, v158
	v_and_b32_e32 v21, 0xffff0000, v158
	v_pk_add_f32 v[6:7], v[6:7], v[20:21]
	v_lshlrev_b32_e32 v20, 16, v159
	v_and_b32_e32 v21, 0xffff0000, v159
	v_pk_add_f32 v[10:11], v[10:11], v[24:25]
	v_pk_add_f32 v[4:5], v[4:5], v[20:21]
	s_mov_b64 exec, s[10:11]
	s_branch .LBB0_1413
